# P3 attention path: 64-byte alignment of loop head and hot branch targets; plus earlier edits
# baseline (speedup 1.0000x reference)
; __global__ void __launch_bounds__(NWAVES * 64, 2) fwd(Args a) {
;     ...
;             v4u qraw[2] = {{0u, 0u, 0u, 0u}, {0u, 0u, 0u, 0u}}; float qss = 0.f;
;             if (wave < 4) { const int qrow0 = base + r0 * 64 + 16 * j + l15; const bf16* qp0 = PROJg + (size_t)(qrow0 - GROWS * grp) * INW + h * 64 + 8 * fq;
;                 qss = hss[(size_t)h * MT + qrow0]; qraw[0] = *(const v4u*)qp0; qraw[1] = *(const v4u*)(qp0 + 32); }
;             f32x4 sc[8]; float mxn = -3e38f; bf16x8 qfn[2] = {};
; #pragma unroll 1
;             for (int st = 0; st < 16; ++st) {
.LBB0_259:
	s_lshl_b32 s53, s33, 1
	s_add_i32 s53, s53, s62
	s_add_i32 s22, s53, 0xffffff00
	s_lshr_b32 s22, s22, 7
	s_add_i32 s22, s22, 8
	s_ashr_i32 s23, s53, 5
	s_add_u32 s54, s91, s54
	s_addc_u32 s55, s92, s55
	s_lshl_b64 s[40:41], s[70:71], 1
	s_add_u32 s58, s24, s40
	s_addc_u32 s59, s25, s41
	v_mov_b32_e32 v141, v3
	v_lshl_add_u64 v[144:145], s[58:59], 0, v[140:141]
	s_add_i32 s58, s60, s56
	s_add_i32 s58, s58, s28
	s_add_i32 s28, s28, s56
	v_add_u32_e32 v139, s28, v188
	v_lshl_add_u64 v[4:5], v[132:133], 0, s[40:41]
	v_add_u32_e32 v137, s28, v190
	v_lshlrev_b32_e32 v141, 6, v139
	s_not_b32 s59, s42
	s_mov_b32 s94, 0
	s_sub_i32 s93, 0, s42
	v_mov_b32_e32 v195, 0xff61b1e6
	s_mov_b32 s85, s42
	s_mov_b32 s87, 0
	s_mov_b32 s40, 0
	v_mov_b32_e32 v75, v74
	v_mov_b32_e32 v76, v74
	v_mov_b32_e32 v77, v74
	v_mov_b32_e32 v78, v74
	v_mov_b32_e32 v79, v74
	v_mov_b32_e32 v80, v74
	v_mov_b32_e32 v81, v74
	s_branch .LBB0_262
	.p2align	6

; __global__ void __launch_bounds__(NWAVES * 64, 2) fwd(Args a) {
;     ...
;             for (int st = 0; st < 16; ++st) {
.LBB0_261:
	s_add_i32 s40, s40, 1
	s_add_i32 s87, s87, 64
	s_add_i32 s85, s85, 1
	s_add_i32 s59, s59, -1
	s_add_i32 s93, s93, -1
	s_add_i32 s94, s94, 2
	s_cmpk_eq_i32 s87, 0x400
	v_add_u32_e32 v141, 0x1000, v141
	s_cbranch_scc1 .LBB0_228
	.p2align	6

; #define LAS __attribute__((address_space(3)))
; #define AT_LDK(KF, RSX, i) do { const LAS unsigned char* kb_ = lds + KRING_OFF + (((RSX) + (i)) % 9) * 8192 + kc0 * 128; \
;                         _Pragma("unroll") for (int cbk = 0; cbk < 2; ++cbk) { KF[cbk][0] = *(const LAS bf16x8*)(kb_ + cbk * 2048 + koff0); KF[cbk][1] = *(const LAS bf16x8*)(kb_ + cbk * 2048 + koff1); } } while (0)
; #define ATT_EXP(t) do { f32x4 e_; e_[0] = __builtin_amdgcn_exp2f(sc[t][0] - mx); e_[1] = __builtin_amdgcn_exp2f(sc[t][1] - mx); e_[2] = __builtin_amdgcn_exp2f(sc[t][2] - mx); e_[3] = __builtin_amdgcn_exp2f(sc[t][3] - mx); \
;                         sc[t] = e_; lsum += (e_[0] + e_[1]) + (e_[2] + e_[3]); } while (0)
; #define AT_PIPE(t, KC, KN) do { \
;                             ATT_LOAD_V(vaA, vbA, t); if ((t) < 7) { AT_LDRB(rkvA, bsvA, rsn_, tbn, t); } if ((t) < 6) { AT_LDK(KN, rsn_, (t) + 1); } \
;                             if ((t) < 7) { AT_MF(KC); } if ((t) < 7) { ATT_EXP((t) + 1); } ATT_COMP_V(vaA, vbA, t); if ((t) < 7) { AT_SC(rkvA, bsvA, t); } } while (0)
; __global__ void __launch_bounds__(NWAVES * 64, 2) fwd(Args a) {
;     ...
;                     if (st < 15) {
;                         const int rsn_ = min(max(r + 1 - 4, 0), rows - 8), dr0n = rsn_ - (r + 1) + 7;
;                         const LAS unsigned char* tbn[4];
; #pragma unroll
;                         for (int e = 0; e < 4; ++e) tbn[e] = (const LAS unsigned char*)(tbl + dr0n * 32) + dsel[e];
;                         AT_BUILDQ(qfn, qraw, qss); mxn = -3e38f;
;                         if (st < 14) { qss = hss[(size_t)h * MT + qrow + 128]; qraw[0] = *(const v4u*)(PROJg + (size_t)(qrow + 128 - GROWS * grp) * INW + h * 64 + 8 * fq); qraw[1] = *(const v4u*)(PROJg + (size_t)(qrow + 128 - GROWS * grp) * INW + h * 64 + 32 + 8 * fq); }
;     ...
;                         AT_LDK(kA, rsn_, 0); ATT_EXP(0); __builtin_amdgcn_sched_barrier(0);
;                         AT_PIPE(0, kA, kB); AT_PIPE(1, kB, kA); AT_PIPE(2, kA, kB); AT_PIPE(3, kB, kA); AT_PIPE(4, kA, kB); AT_PIPE(5, kB, kA); AT_PIPE(6, kA, kB); AT_PIPE(7, kB, kA);
.LBB0_356:
	s_mov_b64 s[70:71], 0
	.p2align	6

; #define LAS __attribute__((address_space(3)))
; #define AT_LDK(KF, RSX, i) do { const LAS unsigned char* kb_ = lds + KRING_OFF + (((RSX) + (i)) % 9) * 8192 + kc0 * 128; \
;                         _Pragma("unroll") for (int cbk = 0; cbk < 2; ++cbk) { KF[cbk][0] = *(const LAS bf16x8*)(kb_ + cbk * 2048 + koff0); KF[cbk][1] = *(const LAS bf16x8*)(kb_ + cbk * 2048 + koff1); } } while (0)
; #define ATT_EXP(t) do { f32x4 e_; e_[0] = __builtin_amdgcn_exp2f(sc[t][0] - mx); e_[1] = __builtin_amdgcn_exp2f(sc[t][1] - mx); e_[2] = __builtin_amdgcn_exp2f(sc[t][2] - mx); e_[3] = __builtin_amdgcn_exp2f(sc[t][3] - mx); \
;                         sc[t] = e_; lsum += (e_[0] + e_[1]) + (e_[2] + e_[3]); } while (0)
; __global__ void __launch_bounds__(NWAVES * 64, 2) fwd(Args a) {
;     ...
;                     if (st < 15) {
;                         const int rsn_ = min(max(r + 1 - 4, 0), rows - 8), dr0n = rsn_ - (r + 1) + 7;
;                         const LAS unsigned char* tbn[4];
; #pragma unroll
;                         for (int e = 0; e < 4; ++e) tbn[e] = (const LAS unsigned char*)(tbl + dr0n * 32) + dsel[e];
;                         AT_BUILDQ(qfn, qraw, qss); mxn = -3e38f;
;                         if (st < 14) { qss = hss[(size_t)h * MT + qrow + 128]; qraw[0] = *(const v4u*)(PROJg + (size_t)(qrow + 128 - GROWS * grp) * INW + h * 64 + 8 * fq); qraw[1] = *(const v4u*)(PROJg + (size_t)(qrow + 128 - GROWS * grp) * INW + h * 64 + 32 + 8 * fq); }
;     ...
;                         AT_LDK(kA, rsn_, 0); ATT_EXP(0); __builtin_amdgcn_sched_barrier(0);
;                         AT_PIPE(0, kA, kB); AT_PIPE(1, kB, kA); AT_PIPE(2, kA, kB); AT_PIPE(3, kB, kA); AT_PIPE(4, kA, kB); AT_PIPE(5, kB, kA); AT_PIPE(6, kA, kB); AT_PIPE(7, kB, kA);
;     ...
;                     } else {
;                         ATT_EXP(0);
; #pragma unroll
;                         for (int t = 0; t < 8; ++t) {
;                             ATT_LOAD_V(vaA, vbA, t); __builtin_amdgcn_sched_barrier(0);
;                             if (t < 7) { ATT_EXP(t + 1); } ATT_COMP_V(vaA, vbA, t); __builtin_amdgcn_sched_barrier(0);
;                         }
;                     }
.LBB0_374:
	s_mov_b64 s[70:71], -1
	.p2align	6

; __global__ void __launch_bounds__(NWAVES * 64, 2) fwd(Args a) {
;     ...
;                         AT_BUILDQ(qfn, qraw, qss); mxn = -3e38f;
;                         if (st < 14) { qss = hss[(size_t)h * MT + qrow + 128]; qraw[0] = *(const v4u*)(PROJg + (size_t)(qrow + 128 - GROWS * grp) * INW + h * 64 + 8 * fq); qraw[1] = *(const v4u*)(PROJg + (size_t)(qrow + 128 - GROWS * grp) * INW + h * 64 + 32 + 8 * fq); }
.Lq_nowait:
	v_mov_b64_e32 v[84:85], v[72:73]
	v_mov_b64_e32 v[88:89], v[68:69]
	s_cmp_gt_u32 s40, 13
	v_mov_b64_e32 v[82:83], v[70:71]
	v_mov_b64_e32 v[86:87], v[66:67]
	v_mov_b32_e32 v147, v194
	s_cbranch_scc1 .LBB0_380
	v_add_u32_e32 v52, s87, v137
	v_add_u32_e32 v52, 0x80, v52
	v_ashrrev_i32_e32 v91, 31, v90
	v_ashrrev_i32_e32 v53, 31, v52
	v_lshl_add_u64 v[50:51], v[90:91], 2, s[54:55]
	v_lshlrev_b64 v[52:53], 12, v[52:53]
	v_lshl_add_u64 v[52:53], v[144:145], 0, v[52:53]
	global_load_dword v147, v[50:51], off offset:512
	global_load_dwordx4 v[82:85], v[52:53], off
	global_load_dwordx4 v[86:89], v[52:53], off offset:64
	.p2align	6
